# GEMM mid-step LDS publish + XOR swizzle, mLSTM stage-2 read hoisting, RWKV step C interleave
# speedup vs baseline: 1.1609x; 1.0076x over previous
.Lrb_done:
	v_add_u32_e32 v64, 0x8000, v91
	v_add_co_u32_e64 v16, s[26:27], s34, 8
	s_waitcnt lgkmcnt(0)
	s_barrier
	v_add_u32_e32 v56, 0x2000, v91
	v_add_u32_e32 v57, 0x8000, v91
	v_add_u32_e32 v58, 0x6000, v91
	v_add_u32_e32 v59, 0x2000, v93
	v_add_u32_e32 v60, 0x8000, v93
	v_add_u32_e32 v61, 0x6000, v93
	ds_read2_b32 v[170:171], v57 offset1:16
	ds_read2_b32 v[172:173], v57 offset0:32 offset1:48
	ds_read2_b32 v[174:175], v56 offset1:16
	ds_read2_b32 v[176:177], v56 offset0:32 offset1:48
	ds_read2_b32 v[178:179], v91 offset1:16
	ds_read2_b32 v[180:181], v91 offset0:32 offset1:48
	ds_read2_b32 v[186:187], v60 offset1:16
	ds_read2_b32 v[188:189], v60 offset0:32 offset1:48
	ds_read2_b32 v[190:191], v59 offset1:16
	ds_read2_b32 v[192:193], v59 offset0:32 offset1:48
	ds_read2_b32 v[194:195], v93 offset1:16
	ds_read2_b32 v[196:197], v93 offset0:32 offset1:48
	v_readfirstlane_b32 s30, v16
	s_and_b64 s[28:29], s[26:27], exec
	s_cselect_b32 s28, s30, s34
	s_cselect_b32 s29, 7, 0x1ff
	s_sub_i32 s29, s29, s28
	s_and_b64 s[26:27], s[26:27], exec
	s_cselect_b32 s31, 0x4000, 0
	s_and_b64 s[26:27], s[64:65], exec
	s_cselect_b32 s26, s28, s29
	s_lshl_b32 s35, s26, 5
	s_add_i32 s35, s35, s31
	s_waitcnt lgkmcnt(6)
	v_add_f32_e32 v206, -1.0, v170
	v_mul_f32_e32 v182, v127, v174
	v_fma_f32 v206, v128, v206, 1.0
	v_mul_f32_e32 v202, v182, v182
	v_mul_f32_e32 v174, v174, v206
	v_mul_f32_e32 v178, v178, v174
	v_mul_f32_e32 v204, v129, v178
	v_add_f32_e32 v206, -1.0, v171
	v_mul_f32_e32 v183, v130, v175
	v_fma_f32 v206, v131, v206, 1.0
	v_fmac_f32_e32 v202, v183, v183
	v_mul_f32_e32 v175, v175, v206
	v_mul_f32_e32 v179, v179, v175
	v_fmac_f32_e32 v204, v132, v179
	v_add_f32_e32 v206, -1.0, v172
	v_mul_f32_e32 v184, v133, v176
	v_fma_f32 v206, v134, v206, 1.0
	v_fmac_f32_e32 v202, v184, v184
	v_mul_f32_e32 v176, v176, v206
	v_mul_f32_e32 v180, v180, v176
	v_fmac_f32_e32 v204, v135, v180
	v_add_f32_e32 v206, -1.0, v173
	v_mul_f32_e32 v185, v136, v177
	v_fma_f32 v206, v137, v206, 1.0
	v_fmac_f32_e32 v202, v185, v185
	v_mul_f32_e32 v177, v177, v206
	v_mul_f32_e32 v181, v181, v177
	v_fmac_f32_e32 v204, v138, v181
	ds_write2_b32 v56, v174, v175 offset1:16
	ds_write2_b32 v56, v176, v177 offset0:32 offset1:48
	s_waitcnt lgkmcnt(2)
	v_add_f32_e32 v207, -1.0, v186
	v_mul_f32_e32 v198, v127, v190
	v_fma_f32 v207, v128, v207, 1.0
	v_mul_f32_e32 v203, v198, v198
	v_mul_f32_e32 v190, v190, v207
	v_mul_f32_e32 v194, v194, v190
	v_mul_f32_e32 v205, v129, v194
	v_add_f32_e32 v207, -1.0, v187
	v_mul_f32_e32 v199, v130, v191
	v_fma_f32 v207, v131, v207, 1.0
	v_fmac_f32_e32 v203, v199, v199
	v_mul_f32_e32 v191, v191, v207
	v_mul_f32_e32 v195, v195, v191
	v_fmac_f32_e32 v205, v132, v195
	v_add_f32_e32 v207, -1.0, v188
	v_mul_f32_e32 v200, v133, v192
	v_fma_f32 v207, v134, v207, 1.0
	v_fmac_f32_e32 v203, v200, v200
	v_mul_f32_e32 v192, v192, v207
	v_mul_f32_e32 v196, v196, v192
	v_fmac_f32_e32 v205, v135, v196
	v_add_f32_e32 v207, -1.0, v189
	v_mul_f32_e32 v201, v136, v193
	v_fma_f32 v207, v137, v207, 1.0
	v_fmac_f32_e32 v203, v201, v201
	v_mul_f32_e32 v193, v193, v207
	v_mul_f32_e32 v197, v197, v193
	v_fmac_f32_e32 v205, v138, v197
	ds_write2_b32 v59, v190, v191 offset1:16
	ds_write2_b32 v59, v192, v193 offset0:32 offset1:48
	s_nop 1
	v_add_f32_dpp v202, v202, v202 quad_perm:[1,0,3,2] row_mask:0xf bank_mask:0xf bound_ctrl:1
	v_add_f32_dpp v203, v203, v203 quad_perm:[1,0,3,2] row_mask:0xf bank_mask:0xf bound_ctrl:1
	v_add_f32_dpp v204, v204, v204 quad_perm:[1,0,3,2] row_mask:0xf bank_mask:0xf bound_ctrl:1
	v_add_f32_dpp v205, v205, v205 quad_perm:[1,0,3,2] row_mask:0xf bank_mask:0xf bound_ctrl:1
	v_add_f32_dpp v202, v202, v202 quad_perm:[2,3,0,1] row_mask:0xf bank_mask:0xf bound_ctrl:1
	v_add_f32_dpp v203, v203, v203 quad_perm:[2,3,0,1] row_mask:0xf bank_mask:0xf bound_ctrl:1
	v_add_f32_dpp v204, v204, v204 quad_perm:[2,3,0,1] row_mask:0xf bank_mask:0xf bound_ctrl:1
	v_add_f32_dpp v205, v205, v205 quad_perm:[2,3,0,1] row_mask:0xf bank_mask:0xf bound_ctrl:1
	v_add_f32_dpp v202, v202, v202 row_half_mirror row_mask:0xf bank_mask:0xf bound_ctrl:1
	v_add_f32_dpp v203, v203, v203 row_half_mirror row_mask:0xf bank_mask:0xf bound_ctrl:1
	v_add_f32_dpp v204, v204, v204 row_half_mirror row_mask:0xf bank_mask:0xf bound_ctrl:1
	v_add_f32_dpp v205, v205, v205 row_half_mirror row_mask:0xf bank_mask:0xf bound_ctrl:1
	v_add_f32_dpp v202, v202, v202 row_mirror row_mask:0xf bank_mask:0xf bound_ctrl:1
	v_add_f32_dpp v203, v203, v203 row_mirror row_mask:0xf bank_mask:0xf bound_ctrl:1
	v_add_f32_dpp v204, v204, v204 row_mirror row_mask:0xf bank_mask:0xf bound_ctrl:1
	v_add_f32_dpp v205, v205, v205 row_mirror row_mask:0xf bank_mask:0xf bound_ctrl:1
	v_sqrt_f32_e32 v202, v202
	v_sqrt_f32_e32 v203, v203
	s_nop 0
	v_max_f32_e32 v202, 0x2b8cbccc, v202
	v_max_f32_e32 v203, 0x2b8cbccc, v203
	v_rcp_f32_e32 v202, v202
	v_rcp_f32_e32 v203, v203
	s_nop 0
	v_mul_f32_e32 v182, v182, v202
	v_mul_f32_e32 v183, v183, v202
	v_mul_f32_e32 v184, v184, v202
	v_mul_f32_e32 v185, v185, v202
	v_mul_f32_e32 v170, v170, v182
	v_mul_f32_e32 v171, v171, v183
	v_mul_f32_e32 v172, v172, v184
	v_mul_f32_e32 v173, v173, v185
	ds_write2_b32 v58, v182, v183 offset1:16
	ds_write2_b32 v58, v184, v185 offset0:32 offset1:48
	ds_write2_b32 v57, v170, v171 offset1:16
	ds_write2_b32 v57, v172, v173 offset0:32 offset1:48
	v_mul_f32_e32 v198, v198, v203
	v_mul_f32_e32 v199, v199, v203
	v_mul_f32_e32 v200, v200, v203
	v_mul_f32_e32 v201, v201, v203
	v_mul_f32_e32 v186, v186, v198
	v_mul_f32_e32 v187, v187, v199
	v_mul_f32_e32 v188, v188, v200
	v_mul_f32_e32 v189, v189, v201
	ds_write2_b32 v61, v198, v199 offset1:16
	ds_write2_b32 v61, v200, v201 offset0:32 offset1:48
	ds_write2_b32 v60, v186, v187 offset1:16
	ds_write2_b32 v60, v188, v189 offset0:32 offset1:48
	s_and_saveexec_b64 s[26:27], s[16:17]
	s_cbranch_execz .LBB0_492
	v_add_u32_e32 v62, s35, v87
	v_ashrrev_i32_e32 v63, 31, v62
	v_lshlrev_b64 v[62:63], 5, v[62:63]
	v_lshl_add_u64 v[62:63], s[78:79], 0, v[62:63]
	global_store_dword v[62:63], v204, off
	v_add_u32_e32 v62, s35, v92
	v_ashrrev_i32_e32 v63, 31, v62
	v_lshlrev_b64 v[62:63], 5, v[62:63]
	v_lshl_add_u64 v[62:63], s[78:79], 0, v[62:63]
	global_store_dword v[62:63], v205, off

.LBB0_829:
	s_or_b64 exec, exec, s[44:45]
	v_sub_co_u32_e64 v16, s[44:45], s77, 8
	s_waitcnt lgkmcnt(14)
	v_mov_b32_e32 v98, s77
	s_and_b64 s[74:75], s[44:45], exec
	v_cndmask_b32_e64 v16, v16, v98, s[44:45]
	s_cselect_b32 s78, 7, 0x1ff
	v_sub_u32_e32 v98, s78, v16
	v_cndmask_b32_e64 v16, v98, v16, s[4:5]
	s_waitcnt lgkmcnt(0)
	s_barrier
	ds_read_b32 v216, v145
	ds_read_b32 v217, v146 offset:64000
	ds_read_b32 v218, v147
	ds_read_b32 v219, v148 offset:65024
	ds_read_b32 v220, v149
	s_cselect_b32 s74, 0x4000, 0
	v_add_u32_e32 v169, s74, v150
	v_add_u32_e32 v170, v143, v135
	v_lshl_add_u32 v222, v16, 5, v169
	v_mov_b32_e32 v221, s89
	ds_read_b32 v171, v221
	ds_read_b128 v[98:101], v170 offset:54272
	ds_read_b128 v[102:105], v151
	ds_read_b128 v[172:175], v151 offset:16
	s_waitcnt lgkmcnt(4)
	v_add_f32_e32 v216, v216, v217
	v_add_f32_e32 v218, v218, v219
	v_max_f32_e32 v220, v220, v220
	v_max_f32_e64 v218, |v218|, v220
	v_rcp_f32_e32 v218, v218
	v_ashrrev_i32_e32 v223, 31, v222
	v_lshlrev_b64 v[222:223], 11, v[222:223]
	v_mul_f32_e32 v216, v216, v218
	v_lshl_add_u64 v[222:223], v[106:107], 0, v[222:223]
	v_cvt_pk_bf16_f32 v220, v216, v17
	global_store_short v[222:223], v220, off
	ds_read_u16 v180, v152 offset:16896
	ds_read_u16 v196, v152 offset:17424
	ds_read_u16 v181, v152 offset:17952
	ds_read_u16 v197, v152 offset:18480
	ds_read_u16 v182, v152 offset:19008
	ds_read_u16 v198, v152 offset:19536
	ds_read_u16 v183, v152 offset:20064
	ds_read_u16 v199, v152 offset:20592
	s_waitcnt lgkmcnt(8)
	v_lshlrev_b32_e32 v176, 16, v98
	v_add_f32_e32 v103, v171, v103
	v_mul_f32_e32 v103, 0x3fb8aa3b, v103
	v_exp_f32_e32 v103, v103
	v_add_f32_e32 v102, v171, v102
	v_mul_f32_e32 v102, 0x3fb8aa3b, v102
	v_and_b32_e32 v98, 0xffff0000, v98
	v_exp_f32_e32 v102, v102
	v_mul_f32_e32 v98, v103, v98
	v_add_f32_e32 v103, v171, v104
	v_mul_f32_e32 v103, 0x3fb8aa3b, v103
	v_exp_f32_e32 v103, v103
	v_mul_f32_e32 v102, v102, v176
	v_cvt_pk_bf16_f32 v98, v102, v98
	v_lshlrev_b32_e32 v102, 16, v99
	v_mul_f32_e32 v102, v103, v102
	v_add_f32_e32 v103, v171, v105
	v_mul_f32_e32 v103, 0x3fb8aa3b, v103
	s_waitcnt lgkmcnt(0)
	v_lshl_or_b32 v180, v196, 16, v180
	v_lshl_or_b32 v181, v197, 16, v181
	v_lshl_or_b32 v182, v198, 16, v182
	v_lshl_or_b32 v183, v199, 16, v183
	ds_read_u16 v184, v152 offset:16928
	ds_read_u16 v200, v152 offset:17456
	ds_read_u16 v185, v152 offset:17984
	ds_read_u16 v201, v152 offset:18512
	ds_read_u16 v186, v152 offset:19040
	ds_read_u16 v202, v152 offset:19568
	ds_read_u16 v187, v152 offset:20096
	ds_read_u16 v203, v152 offset:20624
	v_exp_f32_e32 v103, v103
	v_and_b32_e32 v99, 0xffff0000, v99
	v_mul_f32_e32 v16, 0x3fb8aa3b, v171
	v_exp_f32_e32 v16, v16
	v_mul_f32_e32 v99, v103, v99
	v_add_f32_e32 v103, v171, v172
	v_mul_f32_e32 v103, 0x3fb8aa3b, v103
	v_exp_f32_e32 v103, v103
	v_cvt_pk_bf16_f32 v99, v102, v99
	v_lshlrev_b32_e32 v102, 16, v100
	v_and_b32_e32 v100, 0xffff0000, v100
	v_mul_f32_e32 v102, v103, v102
	v_add_f32_e32 v103, v171, v173
	v_mul_f32_e32 v103, 0x3fb8aa3b, v103
	v_exp_f32_e32 v103, v103
	v_pk_mul_f32 v[96:97], v[96:97], v[16:17] op_sel_hi:[1,0]
	v_pk_mul_f32 v[94:95], v[94:95], v[16:17] op_sel_hi:[1,0]
	v_pk_mul_f32 v[92:93], v[92:93], v[16:17] op_sel_hi:[1,0]
	s_waitcnt lgkmcnt(0)
	v_lshl_or_b32 v184, v200, 16, v184
	v_lshl_or_b32 v185, v201, 16, v185
	v_lshl_or_b32 v186, v202, 16, v186
	v_lshl_or_b32 v187, v203, 16, v187
	ds_read_u16 v188, v152 offset:16960
	ds_read_u16 v204, v152 offset:17488
	ds_read_u16 v189, v152 offset:18016
	ds_read_u16 v205, v152 offset:18544
	ds_read_u16 v190, v152 offset:19072
	ds_read_u16 v206, v152 offset:19600
	ds_read_u16 v191, v152 offset:20128
	ds_read_u16 v207, v152 offset:20656
	v_mul_f32_e32 v100, v103, v100
	v_add_f32_e32 v103, v171, v174
	v_mul_f32_e32 v103, 0x3fb8aa3b, v103
	v_exp_f32_e32 v103, v103
	v_cvt_pk_bf16_f32 v100, v102, v100
	v_lshlrev_b32_e32 v102, 16, v101
	v_and_b32_e32 v101, 0xffff0000, v101
	v_mul_f32_e32 v102, v103, v102
	v_add_f32_e32 v103, v171, v175
	v_mul_f32_e32 v103, 0x3fb8aa3b, v103
	v_exp_f32_e32 v103, v103
	v_pk_mul_f32 v[90:91], v[90:91], v[16:17] op_sel_hi:[1,0]
	v_pk_mul_f32 v[88:89], v[88:89], v[16:17] op_sel_hi:[1,0]
	v_pk_mul_f32 v[86:87], v[86:87], v[16:17] op_sel_hi:[1,0]
	v_mul_f32_e32 v101, v103, v101
	v_cvt_pk_bf16_f32 v101, v102, v101
	v_pk_mul_f32 v[84:85], v[84:85], v[16:17] op_sel_hi:[1,0]
	v_pk_mul_f32 v[82:83], v[82:83], v[16:17] op_sel_hi:[1,0]
	s_waitcnt lgkmcnt(0)
	v_lshl_or_b32 v188, v204, 16, v188
	v_lshl_or_b32 v189, v205, 16, v189
	v_lshl_or_b32 v190, v206, 16, v190
	v_lshl_or_b32 v191, v207, 16, v191
	ds_read_u16 v192, v152 offset:16992
	ds_read_u16 v212, v152 offset:17520
	ds_read_u16 v193, v152 offset:18048
	ds_read_u16 v213, v152 offset:18576
	ds_read_u16 v194, v152 offset:19104
	ds_read_u16 v214, v152 offset:19632
	ds_read_u16 v195, v152 offset:20160
	ds_read_u16 v215, v152 offset:20688
	s_waitcnt lgkmcnt(0)
	v_lshl_or_b32 v192, v212, 16, v192
	v_lshl_or_b32 v193, v213, 16, v193
	v_lshl_or_b32 v194, v214, 16, v194
	v_lshl_or_b32 v195, v215, 16, v195
	s_barrier
	s_nop 1
	v_mfma_f32_16x16x32_bf16 v[94:97], v[98:101], v[180:183], v[94:97]
	v_mfma_f32_16x16x32_bf16 v[90:93], v[98:101], v[184:187], v[90:93]
	v_mfma_f32_16x16x32_bf16 v[86:89], v[98:101], v[188:191], v[86:89]
	v_mfma_f32_16x16x32_bf16 v[82:85], v[98:101], v[192:195], v[82:85]
	s_waitcnt vmcnt(8)
	ds_write_b128 v155, v[46:49]
	s_waitcnt vmcnt(7)
	ds_write_b128 v156, v[50:53]
	s_waitcnt vmcnt(6)
	ds_write_b128 v157, v[54:57]
	s_waitcnt vmcnt(5)
	ds_write_b128 v158, v[58:61]
	s_waitcnt vmcnt(4)
	ds_write_b128 v159, v[66:69]
	s_waitcnt vmcnt(3)
	ds_write_b128 v160, v[70:73]
	s_waitcnt vmcnt(2)
	ds_write_b128 v161, v[74:77]
	s_waitcnt vmcnt(1)
	ds_write_b128 v177, v[78:81]
	s_and_saveexec_b64 s[74:75], s[10:11]
	s_cbranch_execz .LBB0_847

.LBB0_870:
	s_or_b64 exec, exec, s[58:59]
	s_waitcnt lgkmcnt(0)
	s_barrier
	ds_read_b32 v216, v145
	ds_read_b32 v217, v146 offset:64000
	ds_read_b32 v218, v147
	ds_read_b32 v219, v148 offset:65024
	ds_read_b32 v220, v149
	s_add_i32 s58, s77, 1
	s_add_i32 s59, s77, -7
	s_and_b64 s[44:45], s[44:45], exec
	s_cselect_b32 s59, s58, s59
	s_sub_i32 s74, s78, s59
	s_and_b64 s[44:45], s[4:5], exec
	s_cselect_b32 s44, s59, s74
	s_cmpk_gt_u32 s58, 0x206
	v_lshl_add_u32 v222, s44, 5, v169
	v_mov_b32_e32 v221, s89
	ds_read_b32 v172, v221
	ds_read_b128 v[98:101], v170 offset:54272
	ds_read_b128 v[102:105], v151
	ds_read_b128 v[168:171], v151 offset:16
	s_waitcnt lgkmcnt(4)
	v_add_f32_e32 v216, v216, v217
	v_add_f32_e32 v218, v218, v219
	v_max_f32_e32 v220, v220, v220
	v_max_f32_e64 v218, |v218|, v220
	v_rcp_f32_e32 v218, v218
	v_ashrrev_i32_e32 v223, 31, v222
	v_lshlrev_b64 v[222:223], 11, v[222:223]
	v_mul_f32_e32 v216, v216, v218
	v_lshl_add_u64 v[222:223], v[106:107], 0, v[222:223]
	v_cvt_pk_bf16_f32 v220, v216, v17
	global_store_short v[222:223], v220, off
	ds_read_u16 v180, v152 offset:16896
	ds_read_u16 v196, v152 offset:17424
	ds_read_u16 v181, v152 offset:17952
	ds_read_u16 v197, v152 offset:18480
	ds_read_u16 v182, v152 offset:19008
	ds_read_u16 v198, v152 offset:19536
	ds_read_u16 v183, v152 offset:20064
	ds_read_u16 v199, v152 offset:20592
	s_waitcnt lgkmcnt(8)
	v_lshlrev_b32_e32 v173, 16, v98
	v_add_f32_e32 v103, v172, v103
	v_mul_f32_e32 v103, 0x3fb8aa3b, v103
	v_exp_f32_e32 v103, v103
	v_add_f32_e32 v102, v172, v102
	v_mul_f32_e32 v102, 0x3fb8aa3b, v102
	v_and_b32_e32 v98, 0xffff0000, v98
	v_exp_f32_e32 v102, v102
	v_mul_f32_e32 v98, v103, v98
	v_add_f32_e32 v103, v172, v104
	v_mul_f32_e32 v103, 0x3fb8aa3b, v103
	v_exp_f32_e32 v103, v103
	v_mul_f32_e32 v102, v102, v173
	v_cvt_pk_bf16_f32 v98, v102, v98
	v_lshlrev_b32_e32 v102, 16, v99
	v_mul_f32_e32 v102, v103, v102
	v_add_f32_e32 v103, v172, v105
	v_mul_f32_e32 v103, 0x3fb8aa3b, v103
	s_waitcnt lgkmcnt(0)
	v_lshl_or_b32 v180, v196, 16, v180
	v_lshl_or_b32 v181, v197, 16, v181
	v_lshl_or_b32 v182, v198, 16, v182
	v_lshl_or_b32 v183, v199, 16, v183
	ds_read_u16 v184, v152 offset:16928
	ds_read_u16 v200, v152 offset:17456
	ds_read_u16 v185, v152 offset:17984
	ds_read_u16 v201, v152 offset:18512
	ds_read_u16 v186, v152 offset:19040
	ds_read_u16 v202, v152 offset:19568
	ds_read_u16 v187, v152 offset:20096
	ds_read_u16 v203, v152 offset:20624
	v_exp_f32_e32 v103, v103
	v_and_b32_e32 v99, 0xffff0000, v99
	v_mul_f32_e32 v16, 0x3fb8aa3b, v172
	v_exp_f32_e32 v16, v16
	v_mul_f32_e32 v99, v103, v99
	v_add_f32_e32 v103, v172, v168
	v_mul_f32_e32 v103, 0x3fb8aa3b, v103
	v_exp_f32_e32 v103, v103
	v_cvt_pk_bf16_f32 v99, v102, v99
	v_lshlrev_b32_e32 v102, 16, v100
	v_and_b32_e32 v100, 0xffff0000, v100
	v_mul_f32_e32 v102, v103, v102
	v_add_f32_e32 v103, v172, v169
	v_mul_f32_e32 v103, 0x3fb8aa3b, v103
	v_exp_f32_e32 v103, v103
	v_pk_mul_f32 v[96:97], v[96:97], v[16:17] op_sel_hi:[1,0]
	v_pk_mul_f32 v[94:95], v[94:95], v[16:17] op_sel_hi:[1,0]
	v_pk_mul_f32 v[92:93], v[92:93], v[16:17] op_sel_hi:[1,0]
	s_waitcnt lgkmcnt(0)
	v_lshl_or_b32 v184, v200, 16, v184
	v_lshl_or_b32 v185, v201, 16, v185
	v_lshl_or_b32 v186, v202, 16, v186
	v_lshl_or_b32 v187, v203, 16, v187
	ds_read_u16 v188, v152 offset:16960
	ds_read_u16 v204, v152 offset:17488
	ds_read_u16 v189, v152 offset:18016
	ds_read_u16 v205, v152 offset:18544
	ds_read_u16 v190, v152 offset:19072
	ds_read_u16 v206, v152 offset:19600
	ds_read_u16 v191, v152 offset:20128
	ds_read_u16 v207, v152 offset:20656
	v_mul_f32_e32 v100, v103, v100
	v_add_f32_e32 v103, v172, v170
	v_mul_f32_e32 v103, 0x3fb8aa3b, v103
	v_exp_f32_e32 v103, v103
	v_cvt_pk_bf16_f32 v100, v102, v100
	v_lshlrev_b32_e32 v102, 16, v101
	v_and_b32_e32 v101, 0xffff0000, v101
	v_mul_f32_e32 v102, v103, v102
	v_add_f32_e32 v103, v172, v171
	v_mul_f32_e32 v103, 0x3fb8aa3b, v103
	v_exp_f32_e32 v103, v103
	v_pk_mul_f32 v[90:91], v[90:91], v[16:17] op_sel_hi:[1,0]
	v_pk_mul_f32 v[88:89], v[88:89], v[16:17] op_sel_hi:[1,0]
	v_pk_mul_f32 v[86:87], v[86:87], v[16:17] op_sel_hi:[1,0]
	v_mul_f32_e32 v101, v103, v101
	v_cvt_pk_bf16_f32 v101, v102, v101
	v_pk_mul_f32 v[84:85], v[84:85], v[16:17] op_sel_hi:[1,0]
	v_pk_mul_f32 v[82:83], v[82:83], v[16:17] op_sel_hi:[1,0]
	s_waitcnt lgkmcnt(0)
	v_lshl_or_b32 v188, v204, 16, v188
	v_lshl_or_b32 v189, v205, 16, v189
	v_lshl_or_b32 v190, v206, 16, v190
	v_lshl_or_b32 v191, v207, 16, v191
	ds_read_u16 v192, v152 offset:16992
	ds_read_u16 v212, v152 offset:17520
	ds_read_u16 v193, v152 offset:18048
	ds_read_u16 v213, v152 offset:18576
	ds_read_u16 v194, v152 offset:19104
	ds_read_u16 v214, v152 offset:19632
	ds_read_u16 v195, v152 offset:20160
	ds_read_u16 v215, v152 offset:20688
	s_waitcnt lgkmcnt(0)
	v_lshl_or_b32 v192, v212, 16, v192
	v_lshl_or_b32 v193, v213, 16, v193
	v_lshl_or_b32 v194, v214, 16, v194
	v_lshl_or_b32 v195, v215, 16, v195
	s_barrier
	s_nop 1
	v_mfma_f32_16x16x32_bf16 v[94:97], v[98:101], v[180:183], v[94:97]
	v_mfma_f32_16x16x32_bf16 v[90:93], v[98:101], v[184:187], v[90:93]
	v_mfma_f32_16x16x32_bf16 v[86:89], v[98:101], v[188:191], v[86:89]
	v_mfma_f32_16x16x32_bf16 v[82:85], v[98:101], v[192:195], v[82:85]
	s_cbranch_scc1 .LBB0_805
	s_waitcnt vmcnt(9)
	ds_write_b128 v155, v[0:3]
	s_waitcnt vmcnt(8)
	ds_write_b128 v156, v[4:7]
	s_waitcnt vmcnt(7)
	ds_write_b128 v157, v[8:11]
	s_waitcnt vmcnt(6)
	ds_write_b128 v158, v[12:15]
	s_waitcnt vmcnt(5)
	ds_write_b128 v159, v[22:25]
	s_waitcnt vmcnt(4)
	ds_write_b128 v160, v[30:33]
	s_waitcnt vmcnt(3)
	ds_write_b128 v161, v[38:41]
	s_waitcnt vmcnt(2)
	ds_write_b128 v177, v[42:45]
	s_and_saveexec_b64 s[44:45], s[10:11]
	s_cbranch_execz .LBB0_804
	s_branch .LBB0_928

.LBB0_1038:
	s_mul_i32 s42, s45, 0x82
	s_mov_b32 s43, s2
	s_cmp_ge_i32 s43, s42
	s_cbranch_scc1 .LBB0_1739
	v_readlane_b32 s6, v255, 21
	s_cmp_lg_u32 s6, 4
	s_cselect_b64 s[30:31], -1, 0
	s_add_u32 s8, s16, 0x320000
	s_addc_u32 s9, s17, 0
	s_cmp_eq_u32 s6, 0
	s_cselect_b64 s[36:37], -1, 0
	s_cmp_lg_u32 s6, 0
	s_cselect_b64 s[38:39], -1, 0
	s_cmp_lg_u32 s6, 2
	v_writelane_b32 v255, s8, 22
	s_cselect_b64 s[40:41], -1, 0
	s_add_u32 s6, s16, 0xaba8000
	v_writelane_b32 v255, s9, 23
	s_addc_u32 s7, s17, 0
	v_writelane_b32 v255, s6, 24
	v_ashrrev_i32_e32 v3, 1, v0
	v_bfe_u32 v1, v0, 4, 2
	v_writelane_b32 v255, s7, 25
	s_add_u32 s6, s16, 0x8b28000
	s_addc_u32 s7, s17, 0
	s_add_u32 s60, s16, 0x6aa8000
	v_writelane_b32 v255, s6, 26
	s_addc_u32 s61, s17, 0
	v_and_b32_e32 v3, 0xffffffc0, v3
	v_writelane_b32 v255, s7, 27
	s_add_u32 s6, s16, 0xcc28000
	s_addc_u32 s7, s17, 0
	v_writelane_b32 v255, s6, 28
	v_lshl_add_u32 v6, v1, 4, 0
	v_lshl_or_b32 v115, v1, 2, v3
	v_writelane_b32 v255, s7, 29
	v_add_u32_e32 v1, 0x100, v0
	s_add_u32 s78, s16, 0xb3c8000
	v_readlane_b32 s7, v255, 17
	v_ashrrev_i32_e32 v123, 3, v1
	v_add_u32_e32 v1, 0x200, v0
	s_addc_u32 s79, s17, 0
	s_lshl_b32 s6, s7, 4
	v_ashrrev_i32_e32 v132, 3, v1
	v_add_u32_e32 v1, 0x300, v0
	s_and_b32 s80, s6, 0x60
	s_mul_i32 s6, s7, 0x6000
	v_ashrrev_i32_e32 v133, 3, v1
	v_cvt_f32_u32_e32 v1, s45
	s_add_u32 s6, s16, s6
	s_addc_u32 s7, s17, 0
	s_add_u32 s82, s6, 0x102000
	s_addc_u32 s83, s7, 0
	v_rcp_iflag_f32_e32 v1, v1
	s_add_u32 s84, s6, 0x105000
	s_addc_u32 s85, s7, 0
	s_add_u32 s86, s14, 0x118
	v_lshlrev_b32_e32 v2, 3, v0
	s_addc_u32 s87, s15, 0
	v_mul_f32_e32 v1, 0x4f7ffffe, v1
	v_and_b32_e32 v2, 56, v2
	s_add_u32 s6, s14, 16
	v_cvt_u32_f32_e32 v1, v1
	v_lshlrev_b32_e32 v16, 1, v2
	s_addc_u32 s7, s15, 0
	v_add_u32_e32 v4, 0, v16
	v_and_or_b32 v5, v0, 15, v3
	s_cmp_lt_u32 s54, 10
	v_ashrrev_i32_e32 v117, 3, v0
	s_movk_i32 s8, 0x90
	s_cselect_b32 s91, s7, s35
	s_cselect_b32 s90, s6, s34
	v_mad_u64_u32 v[102:103], s[6:7], v117, s8, v[4:5]
	v_mad_u64_u32 v[104:105], s[6:7], v123, s8, v[4:5]
	v_mad_u64_u32 v[106:107], s[6:7], v132, s8, v[4:5]
	v_mad_u64_u32 v[108:109], s[6:7], v133, s8, v[4:5]
	s_cselect_b32 s77, s15, s87
	s_cselect_b32 s76, s14, s86
	s_sub_i32 s6, 0, s45
	v_readfirstlane_b32 s7, v1
	s_mul_i32 s6, s6, s7
	s_mul_hi_u32 s6, s7, s6
	v_and_b32_e32 v113, 0x4f, v0
	s_add_i32 s62, s7, s6
	s_mov_b32 s29, s53
	v_mul_lo_u32 v3, v5, s8
	v_mul_u32_u24_e32 v4, 0x90, v113
	v_and_b32_e32 v0, 7, v0
	s_add_u32 s92, s4, 0x80
	v_lshl_add_u64 v[98:99], s[24:25], 0, v[16:17]
	v_lshl_add_u64 v[100:101], s[4:5], 0, v[16:17]
	s_mov_b32 s81, s53
	v_lshlrev_b32_e32 v110, 4, v0
	v_mov_b32_e32 v111, v17
	s_addc_u32 s93, s5, 0
	s_lshl_b64 s[94:95], s[28:29], 1
	v_lshlrev_b32_e32 v16, 1, v2
	v_add_u32_e32 v134, v6, v3
	v_add_u32_e32 v135, v6, v4
	v_and_b32_e32 v134, 15, v119
	v_bfe_u32 v135, v119, 4, 2
	v_and_b32_e32 v102, 7, v134
	v_xor_b32_e32 v135, v135, v102
	v_lshlrev_b32_e32 v135, 4, v135
	v_lshrrev_b32_e32 v102, 7, v119
	v_lshl_or_b32 v102, v102, 6, v134
	v_lshl_add_u32 v102, v102, 7, v135
	v_bfe_u32 v104, v119, 6, 1
	v_lshl_or_b32 v104, v104, 6, v134
	v_lshl_add_u32 v104, v104, 7, v135
	v_add_u32_e32 v135, 0x4000, v104
	v_mov_b32_e32 v134, v102
	v_xor_b32_e32 v104, 64, v134
	v_xor_b32_e32 v106, 64, v135
	v_lshrrev_b32_e32 v102, 3, v119
	v_and_b32_e32 v108, 7, v102
	v_lshlrev_b32_e32 v102, 7, v102
	v_and_b32_e32 v103, 7, v119
	v_xor_b32_e32 v103, v103, v108
	v_lshl_or_b32 v102, v103, 4, v102
	s_branch .LBB0_1042

.Lg_nsw_pro:
	s_cmp_lt_u32 s6, s44
	s_cselect_b32 s99, s25, s23
	s_cselect_b32 s98, s24, s22
	s_sub_i32 s8, s6, s44
	s_min_u32 s52, s6, s8
	s_lshl_b32 s8, s52, 1
	s_add_u32 s98, s98, s8
	s_addc_u32 s99, s99, 0
	s_sub_i32 s8, s6, 64
	s_lshl_b32 s8, s8, 1
	s_add_u32 s8, s92, s8
	s_addc_u32 s9, s93, 0
	global_load_dwordx4 v[156:159], v128, s[98:99]
	global_load_dwordx4 v[160:163], v124, s[8:9]
	global_load_dwordx4 v[164:167], v129, s[98:99]
	global_load_dwordx4 v[168:171], v125, s[8:9]
	global_load_dwordx4 v[172:175], v130, s[98:99]
	global_load_dwordx4 v[176:179], v126, s[8:9]
	global_load_dwordx4 v[180:183], v131, s[98:99]
	global_load_dwordx4 v[184:187], v127, s[8:9]
	s_add_i32 s6, s6, 64
	s_mov_b32 s11, 0
	s_waitcnt vmcnt(8)
	ds_write_b128 v102, v[66:69]
	ds_write_b128 v102, v[70:73] offset:16384
	ds_write_b128 v102, v[74:77] offset:4096
	ds_write_b128 v102, v[78:81] offset:20480
	ds_write_b128 v102, v[82:85] offset:8192
	ds_write_b128 v102, v[86:89] offset:24576
	ds_write_b128 v102, v[90:93] offset:12288
	ds_write_b128 v102, v[94:97] offset:28672
	s_waitcnt lgkmcnt(0)
	s_barrier
.Lg_A:
	ds_read_b128 v[136:139], v134
	ds_read_b128 v[152:155], v135
	ds_read_b128 v[188:191], v135 offset:2048
	ds_read_b128 v[192:195], v135 offset:4096
	ds_read_b128 v[196:199], v135 offset:6144
	ds_read_b128 v[140:143], v134 offset:2048
	ds_read_b128 v[144:147], v134 offset:4096
	ds_read_b128 v[148:151], v134 offset:6144
	s_cmp_lt_u32 s6, s28
	s_cselect_b32 s7, 1, 0
	s_cbranch_scc0 .Lg_A_nl
	s_cmp_eq_u32 s6, s44
	s_cbranch_scc0 .Lg_nsw_A
	v_lshlrev_b32_e32 v128, 11, v112
	v_lshlrev_b32_e32 v129, 11, v114
	v_lshlrev_b32_e32 v130, 11, v116
	v_lshlrev_b32_e32 v131, 11, v122
	v_add_u32_e32 v128, v128, v16
	v_add_u32_e32 v129, v129, v16
	v_add_u32_e32 v130, v130, v16
	v_add_u32_e32 v131, v131, v16

.Lg_A_nl:
	s_add_i32 s11, s11, 64
	s_waitcnt lgkmcnt(3)
	v_mfma_f32_16x16x32_bf16 v[62:65], v[136:139], v[152:155], v[62:65]
	v_mfma_f32_16x16x32_bf16 v[58:61], v[136:139], v[188:191], v[58:61]
	v_mfma_f32_16x16x32_bf16 v[54:57], v[136:139], v[192:195], v[54:57]
	v_mfma_f32_16x16x32_bf16 v[50:53], v[136:139], v[196:199], v[50:53]
	ds_read_b128 v[200:203], v104
	ds_read_b128 v[220:223], v106
	ds_read_b128 v[230:233], v106 offset:2048
	ds_read_b128 v[234:237], v106 offset:4096
	ds_read_b128 v[244:247], v106 offset:6144
	ds_read_b128 v[204:207], v104 offset:2048
	ds_read_b128 v[212:215], v104 offset:4096
	ds_read_b128 v[216:219], v104 offset:6144
	s_waitcnt lgkmcnt(10)
	v_mfma_f32_16x16x32_bf16 v[46:49], v[140:143], v[152:155], v[46:49]
	v_mfma_f32_16x16x32_bf16 v[42:45], v[140:143], v[188:191], v[42:45]
	v_mfma_f32_16x16x32_bf16 v[38:41], v[140:143], v[192:195], v[38:41]
	v_mfma_f32_16x16x32_bf16 v[34:37], v[140:143], v[196:199], v[34:37]
	s_waitcnt lgkmcnt(9)
	v_mfma_f32_16x16x32_bf16 v[30:33], v[144:147], v[152:155], v[30:33]
	v_mfma_f32_16x16x32_bf16 v[26:29], v[144:147], v[188:191], v[26:29]
	v_mfma_f32_16x16x32_bf16 v[22:25], v[144:147], v[192:195], v[22:25]
	v_mfma_f32_16x16x32_bf16 v[18:21], v[144:147], v[196:199], v[18:21]
	s_waitcnt lgkmcnt(8)
	v_mfma_f32_16x16x32_bf16 v[12:15], v[148:151], v[152:155], v[12:15]
	v_mfma_f32_16x16x32_bf16 v[8:11], v[148:151], v[188:191], v[8:11]
	v_mfma_f32_16x16x32_bf16 v[4:7], v[148:151], v[192:195], v[4:7]
	v_mfma_f32_16x16x32_bf16 v[0:3], v[148:151], v[196:199], v[0:3]
	s_waitcnt lgkmcnt(0)
	s_cmp_ge_u32 s11, s28
	s_cbranch_scc1 .Lg_A_nw
	s_cmp_eq_u32 s7, 0
	s_cbranch_scc1 .Lg_A_w0
	s_waitcnt vmcnt(8)
	s_branch .Lg_A_w

.Lg_A_w:
	ds_write_b128 v102, v[156:159] offset:32768
	ds_write_b128 v102, v[160:163] offset:49152
	ds_write_b128 v102, v[164:167] offset:36864
	ds_write_b128 v102, v[168:171] offset:53248
	ds_write_b128 v102, v[172:175] offset:40960
	ds_write_b128 v102, v[176:179] offset:57344
	ds_write_b128 v102, v[180:183] offset:45056
	ds_write_b128 v102, v[184:187] offset:61440
.Lg_A_nw:
	v_mfma_f32_16x16x32_bf16 v[62:65], v[200:203], v[220:223], v[62:65]
	v_mfma_f32_16x16x32_bf16 v[58:61], v[200:203], v[230:233], v[58:61]
	v_mfma_f32_16x16x32_bf16 v[54:57], v[200:203], v[234:237], v[54:57]
	v_mfma_f32_16x16x32_bf16 v[50:53], v[200:203], v[244:247], v[50:53]
	v_mfma_f32_16x16x32_bf16 v[46:49], v[204:207], v[220:223], v[46:49]
	v_mfma_f32_16x16x32_bf16 v[42:45], v[204:207], v[230:233], v[42:45]
	v_mfma_f32_16x16x32_bf16 v[38:41], v[204:207], v[234:237], v[38:41]
	v_mfma_f32_16x16x32_bf16 v[34:37], v[204:207], v[244:247], v[34:37]
	v_mfma_f32_16x16x32_bf16 v[30:33], v[212:215], v[220:223], v[30:33]
	v_mfma_f32_16x16x32_bf16 v[26:29], v[212:215], v[230:233], v[26:29]
	v_mfma_f32_16x16x32_bf16 v[22:25], v[212:215], v[234:237], v[22:25]
	v_mfma_f32_16x16x32_bf16 v[18:21], v[212:215], v[244:247], v[18:21]
	v_mfma_f32_16x16x32_bf16 v[12:15], v[216:219], v[220:223], v[12:15]
	v_mfma_f32_16x16x32_bf16 v[8:11], v[216:219], v[230:233], v[8:11]
	v_mfma_f32_16x16x32_bf16 v[4:7], v[216:219], v[234:237], v[4:7]
	v_mfma_f32_16x16x32_bf16 v[0:3], v[216:219], v[244:247], v[0:3]
	s_cmp_ge_u32 s11, s28
	s_cbranch_scc1 .Lg_exit
	s_waitcnt lgkmcnt(0)
	s_barrier
.Lg_B:
	ds_read_b128 v[136:139], v134 offset:32768
	ds_read_b128 v[152:155], v135 offset:32768
	ds_read_b128 v[188:191], v135 offset:34816
	ds_read_b128 v[192:195], v135 offset:36864
	ds_read_b128 v[196:199], v135 offset:38912
	ds_read_b128 v[140:143], v134 offset:34816
	ds_read_b128 v[144:147], v134 offset:36864
	ds_read_b128 v[148:151], v134 offset:38912
	s_cmp_lt_u32 s6, s28
	s_cselect_b32 s7, 1, 0
	s_cbranch_scc0 .Lg_B_nl
	s_cmp_eq_u32 s6, s44
	s_cbranch_scc0 .Lg_nsw_B
	v_lshlrev_b32_e32 v128, 11, v112
	v_lshlrev_b32_e32 v129, 11, v114
	v_lshlrev_b32_e32 v130, 11, v116
	v_lshlrev_b32_e32 v131, 11, v122
	v_add_u32_e32 v128, v128, v16
	v_add_u32_e32 v129, v129, v16
	v_add_u32_e32 v130, v130, v16
	v_add_u32_e32 v131, v131, v16

.Lg_B_nl:
	s_add_i32 s11, s11, 64
	s_waitcnt lgkmcnt(3)
	v_mfma_f32_16x16x32_bf16 v[62:65], v[136:139], v[152:155], v[62:65]
	v_mfma_f32_16x16x32_bf16 v[58:61], v[136:139], v[188:191], v[58:61]
	v_mfma_f32_16x16x32_bf16 v[54:57], v[136:139], v[192:195], v[54:57]
	v_mfma_f32_16x16x32_bf16 v[50:53], v[136:139], v[196:199], v[50:53]
	ds_read_b128 v[200:203], v104 offset:32768
	ds_read_b128 v[220:223], v106 offset:32768
	ds_read_b128 v[230:233], v106 offset:34816
	ds_read_b128 v[234:237], v106 offset:36864
	ds_read_b128 v[244:247], v106 offset:38912
	ds_read_b128 v[204:207], v104 offset:34816
	ds_read_b128 v[212:215], v104 offset:36864
	ds_read_b128 v[216:219], v104 offset:38912
	s_waitcnt lgkmcnt(10)
	v_mfma_f32_16x16x32_bf16 v[46:49], v[140:143], v[152:155], v[46:49]
	v_mfma_f32_16x16x32_bf16 v[42:45], v[140:143], v[188:191], v[42:45]
	v_mfma_f32_16x16x32_bf16 v[38:41], v[140:143], v[192:195], v[38:41]
	v_mfma_f32_16x16x32_bf16 v[34:37], v[140:143], v[196:199], v[34:37]
	s_waitcnt lgkmcnt(9)
	v_mfma_f32_16x16x32_bf16 v[30:33], v[144:147], v[152:155], v[30:33]
	v_mfma_f32_16x16x32_bf16 v[26:29], v[144:147], v[188:191], v[26:29]
	v_mfma_f32_16x16x32_bf16 v[22:25], v[144:147], v[192:195], v[22:25]
	v_mfma_f32_16x16x32_bf16 v[18:21], v[144:147], v[196:199], v[18:21]
	s_waitcnt lgkmcnt(8)
	v_mfma_f32_16x16x32_bf16 v[12:15], v[148:151], v[152:155], v[12:15]
	v_mfma_f32_16x16x32_bf16 v[8:11], v[148:151], v[188:191], v[8:11]
	v_mfma_f32_16x16x32_bf16 v[4:7], v[148:151], v[192:195], v[4:7]
	v_mfma_f32_16x16x32_bf16 v[0:3], v[148:151], v[196:199], v[0:3]
	s_waitcnt lgkmcnt(0)
	s_cmp_ge_u32 s11, s28
	s_cbranch_scc1 .Lg_B_nw
	s_cmp_eq_u32 s7, 0
	s_cbranch_scc1 .Lg_B_w0
	s_waitcnt vmcnt(8)
	s_branch .Lg_B_w

.Lg_B_w:
	ds_write_b128 v102, v[66:69]
	ds_write_b128 v102, v[70:73] offset:16384
	ds_write_b128 v102, v[74:77] offset:4096
	ds_write_b128 v102, v[78:81] offset:20480
	ds_write_b128 v102, v[82:85] offset:8192
	ds_write_b128 v102, v[86:89] offset:24576
	ds_write_b128 v102, v[90:93] offset:12288
	ds_write_b128 v102, v[94:97] offset:28672
.Lg_B_nw:
	v_mfma_f32_16x16x32_bf16 v[62:65], v[200:203], v[220:223], v[62:65]
	v_mfma_f32_16x16x32_bf16 v[58:61], v[200:203], v[230:233], v[58:61]
	v_mfma_f32_16x16x32_bf16 v[54:57], v[200:203], v[234:237], v[54:57]
	v_mfma_f32_16x16x32_bf16 v[50:53], v[200:203], v[244:247], v[50:53]
	v_mfma_f32_16x16x32_bf16 v[46:49], v[204:207], v[220:223], v[46:49]
	v_mfma_f32_16x16x32_bf16 v[42:45], v[204:207], v[230:233], v[42:45]
	v_mfma_f32_16x16x32_bf16 v[38:41], v[204:207], v[234:237], v[38:41]
	v_mfma_f32_16x16x32_bf16 v[34:37], v[204:207], v[244:247], v[34:37]
	v_mfma_f32_16x16x32_bf16 v[30:33], v[212:215], v[220:223], v[30:33]
	v_mfma_f32_16x16x32_bf16 v[26:29], v[212:215], v[230:233], v[26:29]
	v_mfma_f32_16x16x32_bf16 v[22:25], v[212:215], v[234:237], v[22:25]
	v_mfma_f32_16x16x32_bf16 v[18:21], v[212:215], v[244:247], v[18:21]
	v_mfma_f32_16x16x32_bf16 v[12:15], v[216:219], v[220:223], v[12:15]
	v_mfma_f32_16x16x32_bf16 v[8:11], v[216:219], v[230:233], v[8:11]
	v_mfma_f32_16x16x32_bf16 v[4:7], v[216:219], v[234:237], v[4:7]
	v_mfma_f32_16x16x32_bf16 v[0:3], v[216:219], v[244:247], v[0:3]
	s_cmp_ge_u32 s11, s28
	s_cbranch_scc1 .Lg_exit
	s_waitcnt lgkmcnt(0)
	s_barrier
	s_branch .Lg_A
